# grid barrier: the first workgroup of each XCD to arrive starts an L2 write-back early so the last arriver's write-back has less to flush
# speedup vs baseline: 1.0045x; 1.0045x over previous
.LBB0_179:
	s_waitcnt lgkmcnt(0)
	v_readfirstlane_b32 s2, v2
	v_readfirstlane_b32 s3, v0
	v_readlane_b32 s6, v255, 46
	s_lshl_b32 s0, s83, 8
	v_readlane_b32 s4, v251, 32
	v_readlane_b32 s5, v251, 33
	v_readlane_b32 s10, v252, 7
	v_readlane_b32 s11, v252, 8
	s_add_i32 s6, s6, 1
	s_add_u32 s0, s4, s0
	s_addc_u32 s1, s5, 0
	v_mov_b32_e32 v3, 0x1000
	v_mov_b32_e32 v4, 1
	v_mov_b32_e32 v5, 0
	v_writelane_b32 v255, s6, 46
	s_mul_i32 s7, s6, s2
	s_mul_i32 s8, s6, s3
	global_atomic_add v1, v3, v4, s[0:1] offset:1024 sc0
	s_mov_b32 s12, 0
	s_waitcnt vmcnt(0)
	v_readfirstlane_b32 s9, v1
	s_add_i32 s9, s9, 1
	s_cmp_lg_u32 s9, s7
	s_cbranch_scc0 .Lgb0_last
	s_sub_i32 s7, s7, s2
	s_add_i32 s7, s7, 1
	s_cmp_lg_u32 s9, s7
	s_cbranch_scc1 .Lgb0_spin
	buffer_wbl2 sc1
	s_branch .Lgb0_spin
.Lgb0_last:
	buffer_wbl2 sc1
	s_waitcnt vmcnt(0)
	global_atomic_add v5, v4, s[10:11]

.LBB0_268:
	s_waitcnt lgkmcnt(0)
	v_readfirstlane_b32 s2, v2
	v_readfirstlane_b32 s3, v0
	v_readlane_b32 s6, v255, 46
	s_lshl_b32 s0, s78, 8
	v_readlane_b32 s4, v251, 32
	v_readlane_b32 s5, v251, 33
	v_readlane_b32 s10, v252, 7
	v_readlane_b32 s11, v252, 8
	s_add_i32 s6, s6, 1
	s_add_u32 s0, s4, s0
	s_addc_u32 s1, s5, 0
	v_mov_b32_e32 v3, 0x1000
	v_mov_b32_e32 v4, 1
	v_mov_b32_e32 v5, 0
	v_writelane_b32 v255, s6, 46
	s_mul_i32 s7, s6, s2
	s_mul_i32 s8, s6, s3
	global_atomic_add v1, v3, v4, s[0:1] offset:1024 sc0
	s_mov_b32 s12, 0
	s_waitcnt vmcnt(0)
	v_readfirstlane_b32 s9, v1
	s_add_i32 s9, s9, 1
	s_cmp_lg_u32 s9, s7
	s_cbranch_scc0 .Lgb1_last
	s_sub_i32 s7, s7, s2
	s_add_i32 s7, s7, 1
	s_cmp_lg_u32 s9, s7
	s_cbranch_scc1 .Lgb1_spin
	buffer_wbl2 sc1
	s_branch .Lgb1_spin

.LBB0_1394:
	s_waitcnt lgkmcnt(0)
	v_readfirstlane_b32 s2, v2
	v_readfirstlane_b32 s3, v0
	v_readlane_b32 s6, v255, 46
	s_lshl_b32 s0, s33, 8
	v_readlane_b32 s4, v251, 32
	v_readlane_b32 s5, v251, 33
	v_readlane_b32 s10, v252, 7
	v_readlane_b32 s11, v252, 8
	s_add_i32 s6, s6, 1
	s_add_u32 s0, s4, s0
	s_addc_u32 s1, s5, 0
	v_mov_b32_e32 v3, 0x1000
	v_mov_b32_e32 v4, 1
	v_mov_b32_e32 v5, 0
	v_writelane_b32 v255, s6, 46
	s_mul_i32 s7, s6, s2
	s_mul_i32 s8, s6, s3
	global_atomic_add v1, v3, v4, s[0:1] offset:1024 sc0
	s_mov_b32 s12, 0
	s_waitcnt vmcnt(0)
	v_readfirstlane_b32 s9, v1
	s_add_i32 s9, s9, 1
	s_cmp_lg_u32 s9, s7
	s_cbranch_scc0 .Lgb11_last
	s_sub_i32 s7, s7, s2
	s_add_i32 s7, s7, 1
	s_cmp_lg_u32 s9, s7
	s_cbranch_scc1 .Lgb11_spin
	buffer_wbl2 sc1
	s_branch .Lgb11_spin
